# v7 + causal attention loop restructured: all waves defer PV one tile, PV(t-1) MFMAs interleaved with softmax(t) VALU in the same wave, separate P registers
# speedup vs baseline: 1.0214x; 1.0078x over previous
.LBB0_1218:
	s_cmp_lt_i32 s44, 11
	s_cselect_b64 s[8:9], -1, 0
	s_and_b64 s[22:23], s[8:9], s[6:7]
	s_andn2_b64 vcc, exec, s[22:23]
	s_cbranch_vccnz .LBB0_1363
	s_add_u32 s3, s42, 0x14804000
	s_addc_u32 s56, s43, 0
	s_add_u32 s57, s42, 0x19004000
	s_addc_u32 s58, s43, 0
	s_add_u32 s59, s42, 0x11804000
	s_addc_u32 s60, s43, 0
	s_add_u32 s61, s42, 0x9004000
	s_addc_u32 s62, s43, 0
	s_add_u32 s63, s42, 0x5004000
	s_addc_u32 s64, s43, 0
	s_add_u32 s65, s42, 0x4944000
	s_addc_u32 s66, s43, 0
	s_add_u32 s67, s42, 0x4a44000
	v_mul_u32_u24_e32 v1, 0x110, v212
	s_addc_u32 s68, s43, 0
	v_add_u32_e32 v0, 0xc800, v215
	s_movk_i32 s70, 0x90
	v_mul_u32_u24_e32 v149, 0x90, v212
	v_add_u32_e32 v146, 0, v214
	v_and_b32_e32 v2, 15, v213
	v_lshlrev_b32_e32 v200, 2, v227
	s_add_i32 s71, 0, 0x20010
	v_lshlrev_b32_e32 v152, 1, v214
	v_add_u32_e32 v214, v215, v1
	v_mbcnt_lo_u32_b32 v1, -1, 0
	v_mov_b32_e32 v145, 0
	v_lshlrev_b32_e32 v147, 4, v228
	s_mov_b32 s25, 0
	s_movk_i32 s69, 0x110
	v_mad_u32_u24 v151, v212, s70, v215
	v_lshl_add_u32 v148, v2, 4, 0
	v_lshlrev_b32_e32 v150, 3, v2
	v_bfe_u32 v199, v213, 4, 2
	v_mul_u32_u24_e32 v201, 0x190, v212
	v_mov_b32_e32 v236, s71
	s_movk_i32 s72, 0x1e00
	s_movk_i32 s73, 0x180
	s_mov_b32 s74, 0x78787879
	s_movk_i32 s75, 0x100
	s_mov_b32 s76, 0x38e38e39
	s_movk_i32 s77, 0x80
	s_add_i32 s78, 0, 0xa400
	s_mov_b64 s[26:27], 0x80
	s_mov_b64 s[28:29], 0x100
	s_mov_b32 s79, 0x41000000
	s_mov_b64 s[30:31], 0x180
	s_mov_b64 s[34:35], 0x1400
	s_movk_i32 s80, 0x1200
	s_mov_b32 s81, 0x51eb851f
	s_mov_b64 s[36:37], 0x48000
	s_add_i32 s83, 0, 0xc400
	v_mbcnt_hi_u32_b32 v237, -1, v1
	v_add_u32_e32 v238, v0, v149
	v_mov_b32_e32 v239, 0xff800000
	s_branch .LBB0_1223

.LBB0_1308:
	s_add_i32 s48, s24, s88
	v_or_b32_e32 v153, s48, v212
	v_add_u32_e32 v40, v215, v201
	ds_read_b128 v[0:3], v40
	ds_read_b128 v[16:19], v40 offset:32
	s_waitcnt lgkmcnt(0)
	v_mfma_f32_32x32x16_bf16 v[0:15], v[0:3], v[96:99], 0
	v_mfma_f32_32x32x16_bf16 v[0:15], v[16:19], v[100:103], v[0:15]
	ds_read_b128 v[16:19], v40 offset:64
	ds_read_b128 v[20:23], v40 offset:96
	s_waitcnt lgkmcnt(0)
	v_mfma_f32_32x32x16_bf16 v[0:15], v[16:19], v[104:107], v[0:15]
	v_mfma_f32_32x32x16_bf16 v[0:15], v[20:23], v[108:111], v[0:15]
	ds_read_b128 v[16:19], v40 offset:128
	ds_read_b128 v[20:23], v40 offset:160
	s_waitcnt lgkmcnt(0)
	v_mfma_f32_32x32x16_bf16 v[0:15], v[16:19], v[112:115], v[0:15]
	v_mfma_f32_32x32x16_bf16 v[0:15], v[20:23], v[116:119], v[0:15]
	ds_read_b128 v[16:19], v40 offset:192
	ds_read_b128 v[20:23], v40 offset:224
	s_waitcnt lgkmcnt(0)
	v_mfma_f32_32x32x16_bf16 v[0:15], v[16:19], v[120:123], v[0:15]
	v_mfma_f32_32x32x16_bf16 v[0:15], v[20:23], v[124:127], v[0:15]
	ds_read_b128 v[16:19], v40 offset:256
	ds_read_b128 v[20:23], v40 offset:288
	s_waitcnt lgkmcnt(0)
	v_mfma_f32_32x32x16_bf16 v[0:15], v[16:19], v[128:131], v[0:15]
	v_mfma_f32_32x32x16_bf16 v[0:15], v[20:23], v[132:135], v[0:15]
	ds_read_b128 v[16:19], v40 offset:320
	ds_read_b128 v[20:23], v40 offset:352
	s_waitcnt lgkmcnt(0)
	v_mfma_f32_32x32x16_bf16 v[0:15], v[16:19], v[136:139], v[0:15]
	v_mfma_f32_32x32x16_bf16 v[0:15], v[20:23], v[140:143], v[0:15]
	ds_read_b128 v[16:19], v40 offset:12800
	ds_read_b128 v[32:35], v40 offset:12832
	s_cmp_gt_u32 s48, 62
	s_waitcnt lgkmcnt(0)
	v_mfma_f32_32x32x16_bf16 v[16:31], v[16:19], v[96:99], 0
	v_mfma_f32_32x32x16_bf16 v[16:31], v[32:35], v[100:103], v[16:31]
	ds_read_b128 v[32:35], v40 offset:12864
	ds_read_b128 v[36:39], v40 offset:12896
	s_waitcnt lgkmcnt(0)
	v_mfma_f32_32x32x16_bf16 v[16:31], v[32:35], v[104:107], v[16:31]
	v_mfma_f32_32x32x16_bf16 v[16:31], v[36:39], v[108:111], v[16:31]
	ds_read_b128 v[32:35], v40 offset:12928
	ds_read_b128 v[36:39], v40 offset:12960
	s_waitcnt lgkmcnt(0)
	v_mfma_f32_32x32x16_bf16 v[16:31], v[32:35], v[112:115], v[16:31]
	v_mfma_f32_32x32x16_bf16 v[16:31], v[36:39], v[116:119], v[16:31]
	ds_read_b128 v[32:35], v40 offset:12992
	ds_read_b128 v[36:39], v40 offset:13024
	s_waitcnt lgkmcnt(0)
	v_mfma_f32_32x32x16_bf16 v[16:31], v[32:35], v[120:123], v[16:31]
	v_mfma_f32_32x32x16_bf16 v[16:31], v[36:39], v[124:127], v[16:31]
	ds_read_b128 v[32:35], v40 offset:13056
	ds_read_b128 v[36:39], v40 offset:13088
	s_waitcnt lgkmcnt(0)
	v_mfma_f32_32x32x16_bf16 v[16:31], v[32:35], v[128:131], v[16:31]
	v_mfma_f32_32x32x16_bf16 v[16:31], v[36:39], v[132:135], v[16:31]
	ds_read_b128 v[32:35], v40 offset:13120
	ds_read_b128 v[36:39], v40 offset:13152
	s_waitcnt lgkmcnt(0)
	v_mfma_f32_32x32x16_bf16 v[16:31], v[32:35], v[136:139], v[16:31]
	v_mfma_f32_32x32x16_bf16 v[16:31], v[36:39], v[140:143], v[16:31]
	s_cbranch_scc1 .LBB0_1310
	v_or_b32_e32 v202, 2, v200
	v_or_b32_e32 v203, 3, v200
	v_or_b32_e32 v204, 8, v200
	v_or_b32_e32 v205, 9, v200
	v_or_b32_e32 v206, 10, v200
	v_or_b32_e32 v207, 11, v200
	v_or_b32_e32 v208, 16, v200
	v_or_b32_e32 v209, 17, v200
	v_or_b32_e32 v210, 18, v200
	v_or_b32_e32 v211, 19, v200
	v_or_b32_e32 v216, 24, v200
	v_or_b32_e32 v217, 25, v200
	v_or_b32_e32 v218, 26, v200
	v_or_b32_e32 v219, 27, v200
	v_or_b32_e32 v220, 32, v200
	v_or_b32_e32 v221, 33, v200
	v_or_b32_e32 v222, 34, v200
	v_or_b32_e32 v223, 35, v200
	v_or_b32_e32 v224, 40, v200
	v_or_b32_e32 v225, 41, v200
	v_or_b32_e32 v226, 42, v200
	v_or_b32_e32 v227, 43, v200
	v_or_b32_e32 v228, 48, v200
	v_or_b32_e32 v229, 49, v200
	v_or_b32_e32 v230, 50, v200
	v_or_b32_e32 v231, 51, v200
	v_or_b32_e32 v232, 56, v200
	v_or_b32_e32 v233, 57, v200
	v_or_b32_e32 v234, 58, v200
	v_or_b32_e32 v235, 59, v200
	v_cmp_gt_u32_e32 vcc, v200, v153
	s_nop 1
	v_cndmask_b32_e32 v32, v0, v239, vcc
	v_cmp_lt_u32_e32 vcc, v200, v153
	s_nop 1
	v_cndmask_b32_e32 v0, v32, v0, vcc
	v_cndmask_b32_e32 v1, v239, v1, vcc
	v_cmp_le_u32_e32 vcc, v202, v153
	s_nop 1
	v_cndmask_b32_e32 v2, v239, v2, vcc
	v_cmp_le_u32_e32 vcc, v203, v153
	s_nop 1
	v_cndmask_b32_e32 v3, v239, v3, vcc
	v_cmp_le_u32_e32 vcc, v204, v153
	s_nop 1
	v_cndmask_b32_e32 v4, v239, v4, vcc
	v_cmp_le_u32_e32 vcc, v205, v153
	s_nop 1
	v_cndmask_b32_e32 v5, v239, v5, vcc
	v_cmp_le_u32_e32 vcc, v206, v153
	s_nop 1
	v_cndmask_b32_e32 v6, v239, v6, vcc
	v_cmp_le_u32_e32 vcc, v207, v153
	s_nop 1
	v_cndmask_b32_e32 v7, v239, v7, vcc
	v_cmp_le_u32_e32 vcc, v208, v153
	s_nop 1
	v_cndmask_b32_e32 v8, v239, v8, vcc
	v_cmp_le_u32_e32 vcc, v209, v153
	s_nop 1
	v_cndmask_b32_e32 v9, v239, v9, vcc
	v_cmp_le_u32_e32 vcc, v210, v153
	s_nop 1
	v_cndmask_b32_e32 v10, v239, v10, vcc
	v_cmp_le_u32_e32 vcc, v211, v153
	s_nop 1
	v_cndmask_b32_e32 v11, v239, v11, vcc
	v_cmp_le_u32_e32 vcc, v216, v153
	s_nop 1
	v_cndmask_b32_e32 v12, v239, v12, vcc
	v_cmp_le_u32_e32 vcc, v217, v153
	s_nop 1
	v_cndmask_b32_e32 v13, v239, v13, vcc
	v_cmp_le_u32_e32 vcc, v218, v153
	s_nop 1
	v_cndmask_b32_e32 v14, v239, v14, vcc
	v_cmp_le_u32_e32 vcc, v219, v153
	s_nop 1
	v_cndmask_b32_e32 v15, v239, v15, vcc
	v_cmp_le_u32_e32 vcc, v220, v153
	s_nop 1
	v_cndmask_b32_e32 v16, v239, v16, vcc
	v_cmp_le_u32_e32 vcc, v221, v153
	s_nop 1
	v_cndmask_b32_e32 v17, v239, v17, vcc
	v_cmp_le_u32_e32 vcc, v222, v153
	s_nop 1
	v_cndmask_b32_e32 v18, v239, v18, vcc
	v_cmp_le_u32_e32 vcc, v223, v153
	s_nop 1
	v_cndmask_b32_e32 v19, v239, v19, vcc
	v_cmp_le_u32_e32 vcc, v224, v153
	s_nop 1
	v_cndmask_b32_e32 v20, v239, v20, vcc
	v_cmp_le_u32_e32 vcc, v225, v153
	s_nop 1
	v_cndmask_b32_e32 v21, v239, v21, vcc
	v_cmp_le_u32_e32 vcc, v226, v153
	s_nop 1
	v_cndmask_b32_e32 v22, v239, v22, vcc
	v_cmp_le_u32_e32 vcc, v227, v153
	s_nop 1
	v_cndmask_b32_e32 v23, v239, v23, vcc
	v_cmp_le_u32_e32 vcc, v228, v153
	s_nop 1
	v_cndmask_b32_e32 v24, v239, v24, vcc
	v_cmp_le_u32_e32 vcc, v229, v153
	s_nop 1
	v_cndmask_b32_e32 v25, v239, v25, vcc
	v_cmp_le_u32_e32 vcc, v230, v153
	s_nop 1
	v_cndmask_b32_e32 v26, v239, v26, vcc
	v_cmp_le_u32_e32 vcc, v231, v153
	s_nop 1
	v_cndmask_b32_e32 v27, v239, v27, vcc
	v_cmp_le_u32_e32 vcc, v232, v153
	s_nop 1
	v_cndmask_b32_e32 v28, v239, v28, vcc
	v_cmp_le_u32_e32 vcc, v233, v153
	s_nop 1
	v_cndmask_b32_e32 v29, v239, v29, vcc
	v_cmp_le_u32_e32 vcc, v234, v153
	s_nop 1
	v_cndmask_b32_e32 v30, v239, v30, vcc
	v_cmp_le_u32_e32 vcc, v235, v153
	s_nop 1
	v_cndmask_b32_e32 v31, v239, v31, vcc
.LBB0_1310:
	v_max_f32_e32 v32, v1, v1
	v_max_f32_e32 v33, v0, v0
	v_max_f32_e32 v32, v33, v32
	v_max3_f32 v32, v32, v2, v3
	v_max3_f32 v32, v32, v4, v5
	v_max3_f32 v32, v32, v6, v7
	v_max3_f32 v32, v32, v8, v9
	v_max3_f32 v32, v32, v10, v11
	v_max3_f32 v32, v32, v12, v13
	v_max3_f32 v32, v32, v14, v15
	s_nop 0
	v_max3_f32 v32, v32, v16, v17
	v_max3_f32 v32, v32, v18, v19
	v_max3_f32 v32, v32, v20, v21
	v_max3_f32 v32, v32, v22, v23
	v_and_b32_e32 v34, 64, v237
	v_max3_f32 v32, v32, v24, v25
	v_xor_b32_e32 v33, 32, v237
	v_add_u32_e32 v34, 64, v34
	v_max3_f32 v32, v32, v26, v27
	v_cmp_lt_i32_e32 vcc, v33, v34
	v_max3_f32 v32, v32, v28, v29
	v_max3_f32 v32, v32, v30, v31
	v_cndmask_b32_e32 v33, v237, v33, vcc
	v_lshlrev_b32_e32 v241, 2, v33
	ds_bpermute_b32 v33, v241, v32
	s_cmp_eq_u32 s52, s52
	s_cselect_b64 s[20:21], -1, 0
	s_cmp_lg_u32 s52, s52
	s_cselect_b64 s[38:39], -1, 0
	s_waitcnt lgkmcnt(0)
	v_max_f32_e32 v33, v33, v33
	v_max_f32_e32 v242, v32, v33
	v_exp_f32_e64 v32, -v242
	v_sub_f32_e32 v31, v31, v242
	v_sub_f32_e32 v0, v0, v242
	v_sub_f32_e32 v1, v1, v242
	v_sub_f32_e32 v2, v2, v242
	v_sub_f32_e32 v3, v3, v242
	v_sub_f32_e32 v4, v4, v242
	v_sub_f32_e32 v5, v5, v242
	v_sub_f32_e32 v6, v6, v242
	v_sub_f32_e32 v7, v7, v242
	v_sub_f32_e32 v8, v8, v242
	v_sub_f32_e32 v9, v9, v242
	v_sub_f32_e32 v10, v10, v242
	v_sub_f32_e32 v11, v11, v242
	v_sub_f32_e32 v12, v12, v242
	v_sub_f32_e32 v13, v13, v242
	v_sub_f32_e32 v14, v14, v242
	v_sub_f32_e32 v15, v15, v242
	v_sub_f32_e32 v16, v16, v242
	v_sub_f32_e32 v17, v17, v242
	v_sub_f32_e32 v18, v18, v242
	v_sub_f32_e32 v19, v19, v242
	v_sub_f32_e32 v20, v20, v242
	v_sub_f32_e32 v21, v21, v242
	v_sub_f32_e32 v22, v22, v242
	v_sub_f32_e32 v23, v23, v242
	v_sub_f32_e32 v24, v24, v242
	v_sub_f32_e32 v25, v25, v242
	v_sub_f32_e32 v26, v26, v242
	v_sub_f32_e32 v27, v27, v242
	v_sub_f32_e32 v28, v28, v242
	v_sub_f32_e32 v29, v29, v242
	v_sub_f32_e32 v30, v30, v242
	v_exp_f32_e32 v154, v0
	v_exp_f32_e32 v155, v1
	v_exp_f32_e32 v168, v2
	v_exp_f32_e32 v169, v3
	v_exp_f32_e32 v170, v4
	v_exp_f32_e32 v171, v5
	v_exp_f32_e32 v172, v6
	v_exp_f32_e32 v173, v7
	v_exp_f32_e32 v174, v8
	v_exp_f32_e32 v175, v9
	v_exp_f32_e32 v176, v10
	v_exp_f32_e32 v177, v11
	v_exp_f32_e32 v178, v12
	v_exp_f32_e32 v179, v13
	v_exp_f32_e32 v180, v14
	v_exp_f32_e32 v181, v15
	v_exp_f32_e32 v182, v16
	v_exp_f32_e32 v183, v17
	v_exp_f32_e32 v184, v18
	v_exp_f32_e32 v185, v19
	v_exp_f32_e32 v186, v20
	v_exp_f32_e32 v187, v21
	v_exp_f32_e32 v188, v22
	v_exp_f32_e32 v189, v23
	v_exp_f32_e32 v190, v24
	v_exp_f32_e32 v191, v25
	v_exp_f32_e32 v192, v26
	v_exp_f32_e32 v193, v27
	v_exp_f32_e32 v194, v28
	v_exp_f32_e32 v195, v29
	v_exp_f32_e32 v196, v30
	v_exp_f32_e32 v197, v31
	v_mul_f32_e32 v64, 0, v32
	v_mov_b32_e32 v65, v64
	v_mov_b32_e32 v66, v64
	v_mov_b32_e32 v67, v64
	v_mov_b32_e32 v68, v64
	v_mov_b32_e32 v69, v64
	v_mov_b32_e32 v70, v64
	v_mov_b32_e32 v71, v64
	v_mov_b32_e32 v72, v64
	v_mov_b32_e32 v73, v64
	v_mov_b32_e32 v74, v64
	v_mov_b32_e32 v75, v64
	v_mov_b32_e32 v76, v64
	v_mov_b32_e32 v77, v64
	v_mov_b32_e32 v78, v64
	v_mov_b32_e32 v79, v64
	v_mov_b64_e32 v[48:49], v[64:65]
	v_mov_b64_e32 v[32:33], v[64:65]
	v_mov_b64_e32 v[16:17], v[64:65]
	v_mov_b64_e32 v[0:1], v[64:65]
	v_cvt_pk_bf16_f32 v92, v154, v155
	v_cvt_pk_bf16_f32 v93, v168, v169
	v_cvt_pk_bf16_f32 v94, v170, v171
	v_cvt_pk_bf16_f32 v95, v172, v173
	v_cvt_pk_bf16_f32 v88, v174, v175
	v_cvt_pk_bf16_f32 v89, v176, v177
	v_cvt_pk_bf16_f32 v90, v178, v179
	v_cvt_pk_bf16_f32 v91, v180, v181
	v_cvt_pk_bf16_f32 v84, v182, v183
	v_cvt_pk_bf16_f32 v85, v184, v185
	v_cvt_pk_bf16_f32 v86, v186, v187
	v_cvt_pk_bf16_f32 v87, v188, v189
	v_cvt_pk_bf16_f32 v80, v190, v191
	v_cvt_pk_bf16_f32 v81, v192, v193
	v_cvt_pk_bf16_f32 v82, v194, v195
	v_cvt_pk_bf16_f32 v83, v196, v197
	s_mov_b32 s52, 1
	s_and_b64 vcc, exec, s[20:21]
	v_mov_b64_e32 v[50:51], v[66:67]
	v_mov_b64_e32 v[52:53], v[68:69]
	v_mov_b64_e32 v[54:55], v[70:71]
	v_mov_b64_e32 v[56:57], v[72:73]
	v_mov_b64_e32 v[58:59], v[74:75]
	v_mov_b64_e32 v[60:61], v[76:77]
	v_mov_b64_e32 v[62:63], v[78:79]
	v_mov_b64_e32 v[34:35], v[66:67]
	v_mov_b64_e32 v[36:37], v[68:69]
	v_mov_b64_e32 v[38:39], v[70:71]
	v_mov_b64_e32 v[40:41], v[72:73]
	v_mov_b64_e32 v[42:43], v[74:75]
	v_mov_b64_e32 v[44:45], v[76:77]
	v_mov_b64_e32 v[46:47], v[78:79]
	v_mov_b64_e32 v[18:19], v[66:67]
	v_mov_b64_e32 v[20:21], v[68:69]
	v_mov_b64_e32 v[22:23], v[70:71]
	v_mov_b64_e32 v[24:25], v[72:73]
	v_mov_b64_e32 v[26:27], v[74:75]
	v_mov_b64_e32 v[28:29], v[76:77]
	v_mov_b64_e32 v[30:31], v[78:79]
	v_mov_b64_e32 v[2:3], v[66:67]
	v_mov_b64_e32 v[4:5], v[68:69]
	v_mov_b64_e32 v[6:7], v[70:71]
	v_mov_b64_e32 v[8:9], v[72:73]
	v_mov_b64_e32 v[10:11], v[74:75]
	v_mov_b64_e32 v[12:13], v[76:77]
	v_mov_b64_e32 v[14:15], v[78:79]
	s_mov_b32 s88, 1
	s_cbranch_vccnz .LBB0_1312
	v_add_u32_e32 v157, v215, v149
	ds_read_b128 v[0:3], v157 offset:51200
	ds_read_b128 v[4:7], v157 offset:55808
	s_waitcnt lgkmcnt(0)
	v_mfma_f32_32x32x16_bf16 v[48:63], v[0:3], v[92:95], v[64:79]
	ds_read_b128 v[0:3], v157 offset:60416
	ds_read_b128 v[244:247], v157 offset:65024
	v_mfma_f32_32x32x16_bf16 v[32:47], v[4:7], v[92:95], v[64:79]
	s_waitcnt lgkmcnt(0)
	v_mfma_f32_32x32x16_bf16 v[16:31], v[0:3], v[92:95], v[64:79]
	v_mov_b64_e32 v[0:1], v[64:65]
	v_mov_b64_e32 v[2:3], v[66:67]
	v_mov_b64_e32 v[4:5], v[68:69]
	v_mov_b64_e32 v[6:7], v[70:71]
	v_mov_b64_e32 v[8:9], v[72:73]
	v_mov_b64_e32 v[10:11], v[74:75]
	v_mov_b64_e32 v[12:13], v[76:77]
	v_mov_b64_e32 v[14:15], v[78:79]
	s_nop 1
	v_mfma_f32_32x32x16_bf16 v[0:15], v[244:247], v[92:95], v[0:15]
	ds_read_b128 v[66:69], v157 offset:51232
	ds_read_b128 v[70:73], v157 offset:55840
	s_waitcnt lgkmcnt(0)
	v_mfma_f32_32x32x16_bf16 v[48:63], v[66:69], v[88:91], v[48:63]
	v_mfma_f32_32x32x16_bf16 v[32:47], v[70:73], v[88:91], v[32:47]
	ds_read_b128 v[66:69], v157 offset:60448
	ds_read_b128 v[70:73], v157 offset:65056
	s_waitcnt lgkmcnt(0)
	v_mfma_f32_32x32x16_bf16 v[16:31], v[66:69], v[88:91], v[16:31]
	v_mfma_f32_32x32x16_bf16 v[0:15], v[70:73], v[88:91], v[0:15]
	ds_read_b128 v[66:69], v157 offset:51264
	ds_read_b128 v[70:73], v157 offset:55872
	s_waitcnt lgkmcnt(0)
	v_mfma_f32_32x32x16_bf16 v[48:63], v[66:69], v[84:87], v[48:63]
	v_mfma_f32_32x32x16_bf16 v[32:47], v[70:73], v[84:87], v[32:47]
	ds_read_b128 v[66:69], v157 offset:60480
	ds_read_b128 v[70:73], v157 offset:65088
	s_waitcnt lgkmcnt(0)
	v_mfma_f32_32x32x16_bf16 v[16:31], v[66:69], v[84:87], v[16:31]
	v_mfma_f32_32x32x16_bf16 v[0:15], v[70:73], v[84:87], v[0:15]
	ds_read_b128 v[66:69], v157 offset:51296
	ds_read_b128 v[70:73], v157 offset:55904
	s_mov_b32 s88, 0
	s_waitcnt lgkmcnt(0)
	v_mfma_f32_32x32x16_bf16 v[48:63], v[66:69], v[80:83], v[48:63]
	v_mfma_f32_32x32x16_bf16 v[32:47], v[70:73], v[80:83], v[32:47]
	ds_read_b128 v[66:69], v157 offset:60512
	ds_read_b128 v[70:73], v157 offset:65120
	s_waitcnt lgkmcnt(0)
	v_mfma_f32_32x32x16_bf16 v[16:31], v[66:69], v[80:83], v[16:31]
	v_mfma_f32_32x32x16_bf16 v[0:15], v[70:73], v[80:83], v[0:15]
.LBB0_1312:
	v_pk_add_f32 v[66:67], v[154:155], 0 op_sel_hi:[1,0]
	s_sub_i32 s33, 0x1000, s53
	v_pk_add_f32 v[66:67], v[168:169], v[66:67]
	s_lshr_b32 s53, s33, 6
	v_pk_add_f32 v[66:67], v[170:171], v[66:67]
	s_mul_hi_u32 s33, s84, 0x15555556
	v_pk_add_f32 v[66:67], v[172:173], v[66:67]
	s_lshl_b32 s49, s54, 7
	v_pk_add_f32 v[66:67], v[174:175], v[66:67]
	s_or_b32 s54, s48, 31
	v_pk_add_f32 v[66:67], v[176:177], v[66:67]
	s_lshl_b32 s55, s55, 10
	v_pk_add_f32 v[66:67], v[178:179], v[66:67]
	s_lshl_b32 s82, s82, 10
	v_pk_add_f32 v[66:67], v[180:181], v[66:67]
	s_lshl_b32 s33, s33, 13
	v_pk_add_f32 v[66:67], v[182:183], v[66:67]
	s_add_u32 s33, s87, s33
	v_pk_add_f32 v[66:67], v[184:185], v[66:67]
	s_addc_u32 s84, 0, 0
	v_pk_add_f32 v[66:67], v[186:187], v[66:67]
	s_add_u32 s90, s33, 0x11804100
	v_pk_add_f32 v[66:67], v[188:189], v[66:67]
	s_addc_u32 s91, s84, 0
	v_pk_add_f32 v[66:67], v[190:191], v[66:67]
	s_add_u32 s33, s86, s85
	v_pk_add_f32 v[66:67], v[192:193], v[66:67]
	s_addc_u32 s85, 0, 0
	v_pk_add_f32 v[66:67], v[194:195], v[66:67]
	s_add_u32 s84, s33, 0x19094000
	v_pk_add_f32 v[66:67], v[196:197], v[66:67]
	v_mov_b32_e32 v161, v145
	v_add_f32_e32 v65, v66, v67
	v_mov_b32_e32 v163, v145
	v_mov_b32_e32 v165, v145
	v_mov_b32_e32 v167, v145
	v_mov_b32_e32 v157, v145
	v_mov_b32_e32 v159, v145
	s_addc_u32 s85, s85, 0
	v_add_f32_e32 v184, v64, v65
	v_lshl_add_u64 v[154:155], s[90:91], 0, v[144:145]
	v_lshl_add_u64 v[156:157], s[90:91], 0, v[156:157]
	v_lshl_add_u64 v[158:159], s[90:91], 0, v[158:159]
	v_lshl_add_u64 v[160:161], s[84:85], 0, v[160:161]
	v_lshl_add_u64 v[162:163], s[84:85], 0, v[162:163]
	v_lshl_add_u64 v[164:165], s[84:85], 0, v[164:165]
	v_lshl_add_u64 v[166:167], s[84:85], 0, v[166:167]
	s_mov_b32 s87, 0
	s_movk_i32 s84, 0x7f
	s_mov_b32 s85, 1
	v_mov_b32_e32 v216, v92
	v_mov_b32_e32 v217, v93
	v_mov_b32_e32 v218, v94
	v_mov_b32_e32 v219, v95
	v_mov_b32_e32 v220, v88
	v_mov_b32_e32 v221, v89
	v_mov_b32_e32 v222, v90
	v_mov_b32_e32 v223, v91
	v_mov_b32_e32 v224, v84
	v_mov_b32_e32 v225, v85
	v_mov_b32_e32 v226, v86
	v_mov_b32_e32 v227, v87
	v_mov_b32_e32 v228, v80
	v_mov_b32_e32 v229, v81
	v_mov_b32_e32 v230, v82
	v_mov_b32_e32 v231, v83
	v_mov_b32_e32 v194, 0
	v_mov_b32_e32 v195, 0
	v_mov_b32_e32 v196, 0
	v_mov_b32_e32 v197, 0

.LBB0_1322:
.LBB0_1324:
	s_sub_i32 s33, s84, 63
	s_cmp_gt_u32 s33, s54
	s_cbranch_scc1 .Lfa_noqk
	v_xor_b32_e32 v64, 0x80000000, v242
	s_mulk_i32 s89, 0x6400
	v_add3_u32 v144, v215, s89, v201
	ds_read_b128 v[168:171], v144
	ds_read_b128 v[172:175], v144 offset:32
	ds_read_b128 v[176:179], v144 offset:64
	ds_read_b128 v[180:183], v144 offset:96
	v_mov_b32_e32 v65, v64
	v_mov_b32_e32 v66, v64
	v_mov_b32_e32 v67, v64
	v_mov_b32_e32 v68, v64
	v_mov_b32_e32 v69, v64
	v_mov_b32_e32 v70, v64
	v_mov_b32_e32 v71, v64
	v_mov_b32_e32 v72, v64
	v_mov_b32_e32 v73, v64
	v_mov_b32_e32 v74, v64
	v_mov_b32_e32 v75, v64
	v_mov_b32_e32 v76, v64
	v_mov_b32_e32 v77, v64
	v_mov_b32_e32 v78, v64
	v_mov_b32_e32 v79, v64
	s_nop 1
	s_waitcnt lgkmcnt(3)
	v_mfma_f32_32x32x16_bf16 v[80:95], v[168:171], v[96:99], v[64:79]
	ds_read_b128 v[168:171], v144 offset:128
	s_waitcnt lgkmcnt(3)
	v_mfma_f32_32x32x16_bf16 v[80:95], v[172:175], v[100:103], v[80:95]
	ds_read_b128 v[172:175], v144 offset:160
	s_waitcnt lgkmcnt(3)
	v_mfma_f32_32x32x16_bf16 v[80:95], v[176:179], v[104:107], v[80:95]
	ds_read_b128 v[176:179], v144 offset:192
	s_waitcnt lgkmcnt(3)
	v_mfma_f32_32x32x16_bf16 v[80:95], v[180:183], v[108:111], v[80:95]
	ds_read_b128 v[180:183], v144 offset:224
	s_waitcnt lgkmcnt(3)
	v_mfma_f32_32x32x16_bf16 v[80:95], v[168:171], v[112:115], v[80:95]
	ds_read_b128 v[168:171], v144 offset:256
	s_waitcnt lgkmcnt(3)
	v_mfma_f32_32x32x16_bf16 v[80:95], v[172:175], v[116:119], v[80:95]
	ds_read_b128 v[172:175], v144 offset:288
	s_waitcnt lgkmcnt(3)
	v_mfma_f32_32x32x16_bf16 v[80:95], v[176:179], v[120:123], v[80:95]
	ds_read_b128 v[176:179], v144 offset:320
	s_waitcnt lgkmcnt(3)
	v_mfma_f32_32x32x16_bf16 v[80:95], v[180:183], v[124:127], v[80:95]
	ds_read_b128 v[180:183], v144 offset:352
	s_waitcnt lgkmcnt(3)
	v_mfma_f32_32x32x16_bf16 v[80:95], v[168:171], v[128:131], v[80:95]
	ds_read_b128 v[168:171], v144 offset:12800
	s_waitcnt lgkmcnt(3)
	v_mfma_f32_32x32x16_bf16 v[80:95], v[172:175], v[132:135], v[80:95]
	ds_read_b128 v[172:175], v144 offset:12832
	s_waitcnt lgkmcnt(3)
	v_mfma_f32_32x32x16_bf16 v[80:95], v[176:179], v[136:139], v[80:95]
	ds_read_b128 v[176:179], v144 offset:12864
	s_waitcnt lgkmcnt(3)
	v_mfma_f32_32x32x16_bf16 v[80:95], v[180:183], v[140:143], v[80:95]
	ds_read_b128 v[180:183], v144 offset:12896
	s_waitcnt lgkmcnt(3)
	v_mfma_f32_32x32x16_bf16 v[64:79], v[168:171], v[96:99], v[64:79]
	ds_read_b128 v[168:171], v144 offset:12928
	s_waitcnt lgkmcnt(3)
	v_mfma_f32_32x32x16_bf16 v[64:79], v[172:175], v[100:103], v[64:79]
	ds_read_b128 v[172:175], v144 offset:12960
	s_waitcnt lgkmcnt(3)
	v_mfma_f32_32x32x16_bf16 v[64:79], v[176:179], v[104:107], v[64:79]
	ds_read_b128 v[176:179], v144 offset:12992
	s_waitcnt lgkmcnt(3)
	v_mfma_f32_32x32x16_bf16 v[64:79], v[180:183], v[108:111], v[64:79]
	ds_read_b128 v[180:183], v144 offset:13024
	s_waitcnt lgkmcnt(3)
	v_mfma_f32_32x32x16_bf16 v[64:79], v[168:171], v[112:115], v[64:79]
	ds_read_b128 v[168:171], v144 offset:13056
	s_waitcnt lgkmcnt(3)
	v_mfma_f32_32x32x16_bf16 v[64:79], v[172:175], v[116:119], v[64:79]
	ds_read_b128 v[172:175], v144 offset:13088
	s_waitcnt lgkmcnt(3)
	v_mfma_f32_32x32x16_bf16 v[64:79], v[176:179], v[120:123], v[64:79]
	ds_read_b128 v[176:179], v144 offset:13120
	s_waitcnt lgkmcnt(3)
	v_mfma_f32_32x32x16_bf16 v[64:79], v[180:183], v[124:127], v[64:79]
	ds_read_b128 v[180:183], v144 offset:13152
	s_waitcnt lgkmcnt(3)
	v_mfma_f32_32x32x16_bf16 v[64:79], v[168:171], v[128:131], v[64:79]
	s_waitcnt lgkmcnt(2)
	v_mfma_f32_32x32x16_bf16 v[64:79], v[172:175], v[132:135], v[64:79]
	s_waitcnt lgkmcnt(1)
	v_mfma_f32_32x32x16_bf16 v[64:79], v[176:179], v[136:139], v[64:79]
	s_waitcnt lgkmcnt(0)
	v_mfma_f32_32x32x16_bf16 v[64:79], v[180:183], v[140:143], v[64:79]
	s_cmp_le_u32 s84, s48
	s_cbranch_scc1 .LBB0_1327
	v_add_u32_e32 v144, s84, v200
	v_subrev_u32_e32 v168, 63, v144
	v_cmp_gt_u32_e32 vcc, v168, v153
	s_nop 1
	v_cndmask_b32_e32 v169, v80, v239, vcc
	v_cmp_lt_u32_e32 vcc, v168, v153
	v_subrev_u32_e32 v168, 61, v144
	s_nop 0
	v_cndmask_b32_e32 v80, v169, v80, vcc
	v_cndmask_b32_e32 v81, v239, v81, vcc
	v_cmp_le_u32_e32 vcc, v168, v153
	v_subrev_u32_e32 v168, 60, v144
	s_nop 0
	v_cndmask_b32_e32 v82, v239, v82, vcc
	v_cmp_le_u32_e32 vcc, v168, v153
	v_subrev_u32_e32 v168, 55, v144
	s_nop 0
	v_cndmask_b32_e32 v83, v239, v83, vcc
	v_cmp_le_u32_e32 vcc, v168, v153
	v_subrev_u32_e32 v168, 54, v144
	s_nop 0
	v_cndmask_b32_e32 v84, v239, v84, vcc
	v_cmp_le_u32_e32 vcc, v168, v153
	v_subrev_u32_e32 v168, 53, v144
	s_nop 0
	v_cndmask_b32_e32 v85, v239, v85, vcc
	v_cmp_le_u32_e32 vcc, v168, v153
	v_subrev_u32_e32 v168, 52, v144
	s_nop 0
	v_cndmask_b32_e32 v86, v239, v86, vcc
	v_cmp_le_u32_e32 vcc, v168, v153
	v_subrev_u32_e32 v168, 47, v144
	s_nop 0
	v_cndmask_b32_e32 v87, v239, v87, vcc
	v_cmp_le_u32_e32 vcc, v168, v153
	v_subrev_u32_e32 v168, 46, v144
	s_nop 0
	v_cndmask_b32_e32 v88, v239, v88, vcc
	v_cmp_le_u32_e32 vcc, v168, v153
	v_subrev_u32_e32 v168, 45, v144
	s_nop 0
	v_cndmask_b32_e32 v89, v239, v89, vcc
	v_cmp_le_u32_e32 vcc, v168, v153
	v_subrev_u32_e32 v168, 44, v144
	s_nop 0
	v_cndmask_b32_e32 v90, v239, v90, vcc
	v_cmp_le_u32_e32 vcc, v168, v153
	v_subrev_u32_e32 v168, 39, v144
	s_nop 0
	v_cndmask_b32_e32 v91, v239, v91, vcc
	v_cmp_le_u32_e32 vcc, v168, v153
	v_subrev_u32_e32 v168, 38, v144
	s_nop 0
	v_cndmask_b32_e32 v92, v239, v92, vcc
	v_cmp_le_u32_e32 vcc, v168, v153
	v_subrev_u32_e32 v168, 37, v144
	s_nop 0
	v_cndmask_b32_e32 v93, v239, v93, vcc
	v_cmp_le_u32_e32 vcc, v168, v153
	v_subrev_u32_e32 v168, 36, v144
	s_nop 0
	v_cndmask_b32_e32 v94, v239, v94, vcc
	v_cmp_le_u32_e32 vcc, v168, v153
	v_subrev_u32_e32 v168, 31, v144
	s_nop 0
	v_cndmask_b32_e32 v95, v239, v95, vcc
	v_cmp_le_u32_e32 vcc, v168, v153
	v_subrev_u32_e32 v168, 30, v144
	s_nop 0
	v_cndmask_b32_e32 v64, v239, v64, vcc
	v_cmp_le_u32_e32 vcc, v168, v153
	v_subrev_u32_e32 v168, 29, v144
	s_nop 0
	v_cndmask_b32_e32 v65, v239, v65, vcc
	v_cmp_le_u32_e32 vcc, v168, v153
	v_subrev_u32_e32 v168, 28, v144
	s_nop 0
	v_cndmask_b32_e32 v66, v239, v66, vcc
	v_cmp_le_u32_e32 vcc, v168, v153
	v_subrev_u32_e32 v168, 23, v144
	s_nop 0
	v_cndmask_b32_e32 v67, v239, v67, vcc
	v_cmp_le_u32_e32 vcc, v168, v153
	v_subrev_u32_e32 v168, 22, v144
	s_nop 0
	v_cndmask_b32_e32 v68, v239, v68, vcc
	v_cmp_le_u32_e32 vcc, v168, v153
	v_subrev_u32_e32 v168, 21, v144
	s_nop 0
	v_cndmask_b32_e32 v69, v239, v69, vcc
	v_cmp_le_u32_e32 vcc, v168, v153
	v_subrev_u32_e32 v168, 20, v144
	s_nop 0
	v_cndmask_b32_e32 v70, v239, v70, vcc
	v_cmp_le_u32_e32 vcc, v168, v153
	v_add_u32_e32 v168, -15, v144
	s_nop 0
	v_cndmask_b32_e32 v71, v239, v71, vcc
	v_cmp_le_u32_e32 vcc, v168, v153
	v_add_u32_e32 v168, -14, v144
	s_nop 0
	v_cndmask_b32_e32 v72, v239, v72, vcc
	v_cmp_le_u32_e32 vcc, v168, v153
	v_add_u32_e32 v168, -13, v144
	s_nop 0
	v_cndmask_b32_e32 v73, v239, v73, vcc
	v_cmp_le_u32_e32 vcc, v168, v153
	v_add_u32_e32 v168, -12, v144
	s_nop 0
	v_cndmask_b32_e32 v74, v239, v74, vcc
	v_cmp_le_u32_e32 vcc, v168, v153
	v_add_u32_e32 v168, -7, v144
	s_nop 0
	v_cndmask_b32_e32 v75, v239, v75, vcc
	v_cmp_le_u32_e32 vcc, v168, v153
	v_add_u32_e32 v168, -6, v144
	s_nop 0
	v_cndmask_b32_e32 v76, v239, v76, vcc
	v_cmp_le_u32_e32 vcc, v168, v153
	v_add_u32_e32 v168, -5, v144
	v_add_u32_e32 v144, -4, v144
	v_cndmask_b32_e32 v77, v239, v77, vcc
	v_cmp_le_u32_e32 vcc, v168, v153
	s_nop 1
	v_cndmask_b32_e32 v78, v239, v78, vcc
	v_cmp_le_u32_e32 vcc, v144, v153
	s_nop 1
	v_cndmask_b32_e32 v79, v239, v79, vcc
.LBB0_1327:
	v_max_f32_e32 v144, v81, v81
	v_max_f32_e32 v168, v80, v80
	v_max_f32_e32 v144, v168, v144
	v_max3_f32 v144, v144, v82, v83
	v_max3_f32 v144, v144, v84, v85
	v_max3_f32 v144, v144, v86, v87
	v_max3_f32 v144, v144, v88, v89
	v_max3_f32 v144, v144, v90, v91
	v_max3_f32 v144, v144, v92, v93
	v_max3_f32 v144, v144, v94, v95
	s_nop 0
	v_max3_f32 v144, v144, v64, v65
	v_max3_f32 v144, v144, v66, v67
	v_max3_f32 v144, v144, v68, v69
	v_max3_f32 v144, v144, v70, v71
	v_max3_f32 v144, v144, v72, v73
	v_max3_f32 v144, v144, v74, v75
	v_max3_f32 v144, v144, v76, v77
	v_max3_f32 v144, v144, v78, v79
	ds_bpermute_b32 v168, v241, v144
	s_waitcnt lgkmcnt(0)
	v_max_f32_e32 v168, v168, v168
	v_max_f32_e32 v144, v144, v168
	v_cmp_lt_f32_e32 vcc, s79, v144
	s_cbranch_vccnz .Lfa_rare
	s_mul_i32 s33, s87, 0x4800
	v_add_u32_e32 v243, s33, v151
	ds_read_b128 v[232:235], v243 offset:51200
	ds_read_b128 v[202:205], v243 offset:55808
	ds_read_b128 v[206:209], v243 offset:60416
	ds_read_b128 v[244:247], v243 offset:65024
	s_waitcnt lgkmcnt(3)
	v_mfma_f32_32x32x16_bf16 v[48:63], v[232:235], v[216:219], v[48:63]
	ds_read_b128 v[232:235], v243 offset:51232
	v_exp_f32_e32 v168, v80
	v_exp_f32_e32 v169, v81
	s_waitcnt lgkmcnt(3)
	v_mfma_f32_32x32x16_bf16 v[32:47], v[202:205], v[216:219], v[32:47]
	ds_read_b128 v[202:205], v243 offset:55840
	v_exp_f32_e32 v170, v82
	v_exp_f32_e32 v171, v83
	s_waitcnt lgkmcnt(3)
	v_mfma_f32_32x32x16_bf16 v[16:31], v[206:209], v[216:219], v[16:31]
	ds_read_b128 v[206:209], v243 offset:60448
	v_exp_f32_e32 v172, v84
	v_exp_f32_e32 v173, v85
	s_waitcnt lgkmcnt(3)
	v_mfma_f32_32x32x16_bf16 v[0:15], v[244:247], v[216:219], v[0:15]
	ds_read_b128 v[244:247], v243 offset:65056
	v_exp_f32_e32 v174, v86
	v_exp_f32_e32 v175, v87
	s_waitcnt lgkmcnt(3)
	v_mfma_f32_32x32x16_bf16 v[48:63], v[232:235], v[220:223], v[48:63]
	ds_read_b128 v[232:235], v243 offset:51264
	v_exp_f32_e32 v176, v88
	v_exp_f32_e32 v177, v89
	v_cvt_pk_bf16_f32 v216, v168, v169
	v_pk_add_f32 v[194:195], v[194:195], v[168:169]
	s_waitcnt lgkmcnt(3)
	v_mfma_f32_32x32x16_bf16 v[32:47], v[202:205], v[220:223], v[32:47]
	ds_read_b128 v[202:205], v243 offset:55872
	v_exp_f32_e32 v178, v90
	v_exp_f32_e32 v179, v91
	v_cvt_pk_bf16_f32 v217, v170, v171
	v_pk_add_f32 v[196:197], v[196:197], v[170:171]
	s_waitcnt lgkmcnt(3)
	v_mfma_f32_32x32x16_bf16 v[16:31], v[206:209], v[220:223], v[16:31]
	ds_read_b128 v[206:209], v243 offset:60480
	v_exp_f32_e32 v180, v92
	v_exp_f32_e32 v181, v93
	v_cvt_pk_bf16_f32 v218, v172, v173
	v_pk_add_f32 v[194:195], v[194:195], v[172:173]
	s_waitcnt lgkmcnt(3)
	v_mfma_f32_32x32x16_bf16 v[0:15], v[244:247], v[220:223], v[0:15]
	ds_read_b128 v[244:247], v243 offset:65088
	v_exp_f32_e32 v182, v94
	v_exp_f32_e32 v183, v95
	v_cvt_pk_bf16_f32 v219, v174, v175
	v_pk_add_f32 v[196:197], v[196:197], v[174:175]
	s_waitcnt lgkmcnt(3)
	v_mfma_f32_32x32x16_bf16 v[48:63], v[232:235], v[224:227], v[48:63]
	ds_read_b128 v[232:235], v243 offset:51296
	v_exp_f32_e32 v64, v64
	v_exp_f32_e32 v65, v65
	v_cvt_pk_bf16_f32 v220, v176, v177
	v_pk_add_f32 v[194:195], v[194:195], v[176:177]
	s_waitcnt lgkmcnt(3)
	v_mfma_f32_32x32x16_bf16 v[32:47], v[202:205], v[224:227], v[32:47]
	ds_read_b128 v[202:205], v243 offset:55904
	v_exp_f32_e32 v66, v66
	v_exp_f32_e32 v67, v67
	v_cvt_pk_bf16_f32 v221, v178, v179
	v_pk_add_f32 v[196:197], v[196:197], v[178:179]
	s_waitcnt lgkmcnt(3)
	v_mfma_f32_32x32x16_bf16 v[16:31], v[206:209], v[224:227], v[16:31]
	ds_read_b128 v[206:209], v243 offset:60512
	v_exp_f32_e32 v68, v68
	v_exp_f32_e32 v69, v69
	v_cvt_pk_bf16_f32 v222, v180, v181
	v_pk_add_f32 v[194:195], v[194:195], v[180:181]
	s_waitcnt lgkmcnt(3)
	v_mfma_f32_32x32x16_bf16 v[0:15], v[244:247], v[224:227], v[0:15]
	ds_read_b128 v[244:247], v243 offset:65120
	v_exp_f32_e32 v70, v70
	v_exp_f32_e32 v71, v71
	v_cvt_pk_bf16_f32 v223, v182, v183
	v_pk_add_f32 v[196:197], v[196:197], v[182:183]
	s_waitcnt lgkmcnt(3)
	v_mfma_f32_32x32x16_bf16 v[48:63], v[232:235], v[228:231], v[48:63]
	v_exp_f32_e32 v72, v72
	v_exp_f32_e32 v73, v73
	v_cvt_pk_bf16_f32 v224, v64, v65
	v_pk_add_f32 v[194:195], v[194:195], v[64:65]
	s_waitcnt lgkmcnt(2)
	v_mfma_f32_32x32x16_bf16 v[32:47], v[202:205], v[228:231], v[32:47]
	v_exp_f32_e32 v74, v74
	v_exp_f32_e32 v75, v75
	v_cvt_pk_bf16_f32 v225, v66, v67
	v_pk_add_f32 v[196:197], v[196:197], v[66:67]
	s_waitcnt lgkmcnt(1)
	v_mfma_f32_32x32x16_bf16 v[16:31], v[206:209], v[228:231], v[16:31]
	v_exp_f32_e32 v76, v76
	v_exp_f32_e32 v77, v77
	v_cvt_pk_bf16_f32 v226, v68, v69
	v_pk_add_f32 v[194:195], v[194:195], v[68:69]
	s_waitcnt lgkmcnt(0)
	v_mfma_f32_32x32x16_bf16 v[0:15], v[244:247], v[228:231], v[0:15]
	v_exp_f32_e32 v78, v78
	v_exp_f32_e32 v79, v79
	v_cvt_pk_bf16_f32 v227, v70, v71
	v_pk_add_f32 v[196:197], v[196:197], v[70:71]
	v_cvt_pk_bf16_f32 v228, v72, v73
	v_pk_add_f32 v[194:195], v[194:195], v[72:73]
	v_cvt_pk_bf16_f32 v229, v74, v75
	v_pk_add_f32 v[196:197], v[196:197], v[74:75]
	v_cvt_pk_bf16_f32 v230, v76, v77
	v_pk_add_f32 v[194:195], v[194:195], v[76:77]
	v_cvt_pk_bf16_f32 v231, v78, v79
	v_pk_add_f32 v[196:197], v[196:197], v[78:79]
	s_mov_b32 s88, 1
	s_branch .LBB0_1332
.Lfa_rare:
	s_cmp_eq_u32 s88, 0
	s_cbranch_scc1 .Lfa_rare2
	s_mul_i32 s33, s87, 0x4800
	v_add_u32_e32 v243, s33, v151
	ds_read_b128 v[232:235], v243 offset:51200
	ds_read_b128 v[202:205], v243 offset:55808
	ds_read_b128 v[206:209], v243 offset:60416
	ds_read_b128 v[244:247], v243 offset:65024
	s_waitcnt lgkmcnt(3)
	v_mfma_f32_32x32x16_bf16 v[48:63], v[232:235], v[216:219], v[48:63]
	ds_read_b128 v[232:235], v243 offset:51232
	s_waitcnt lgkmcnt(3)
	v_mfma_f32_32x32x16_bf16 v[32:47], v[202:205], v[216:219], v[32:47]
	ds_read_b128 v[202:205], v243 offset:55840
	s_waitcnt lgkmcnt(3)
	v_mfma_f32_32x32x16_bf16 v[16:31], v[206:209], v[216:219], v[16:31]
	ds_read_b128 v[206:209], v243 offset:60448
	s_waitcnt lgkmcnt(3)
	v_mfma_f32_32x32x16_bf16 v[0:15], v[244:247], v[216:219], v[0:15]
	ds_read_b128 v[244:247], v243 offset:65056
	s_waitcnt lgkmcnt(3)
	v_mfma_f32_32x32x16_bf16 v[48:63], v[232:235], v[220:223], v[48:63]
	ds_read_b128 v[232:235], v243 offset:51264
	s_waitcnt lgkmcnt(3)
	v_mfma_f32_32x32x16_bf16 v[32:47], v[202:205], v[220:223], v[32:47]
	ds_read_b128 v[202:205], v243 offset:55872
	s_waitcnt lgkmcnt(3)
	v_mfma_f32_32x32x16_bf16 v[16:31], v[206:209], v[220:223], v[16:31]
	ds_read_b128 v[206:209], v243 offset:60480
	s_waitcnt lgkmcnt(3)
	v_mfma_f32_32x32x16_bf16 v[0:15], v[244:247], v[220:223], v[0:15]
	ds_read_b128 v[244:247], v243 offset:65088
	s_waitcnt lgkmcnt(3)
	v_mfma_f32_32x32x16_bf16 v[48:63], v[232:235], v[224:227], v[48:63]
	ds_read_b128 v[232:235], v243 offset:51296
	s_waitcnt lgkmcnt(3)
	v_mfma_f32_32x32x16_bf16 v[32:47], v[202:205], v[224:227], v[32:47]
	ds_read_b128 v[202:205], v243 offset:55904
	s_waitcnt lgkmcnt(3)
	v_mfma_f32_32x32x16_bf16 v[16:31], v[206:209], v[224:227], v[16:31]
	ds_read_b128 v[206:209], v243 offset:60512
	s_waitcnt lgkmcnt(3)
	v_mfma_f32_32x32x16_bf16 v[0:15], v[244:247], v[224:227], v[0:15]
	ds_read_b128 v[244:247], v243 offset:65120
	s_waitcnt lgkmcnt(3)
	v_mfma_f32_32x32x16_bf16 v[48:63], v[232:235], v[228:231], v[48:63]
	s_waitcnt lgkmcnt(2)
	v_mfma_f32_32x32x16_bf16 v[32:47], v[202:205], v[228:231], v[32:47]
	s_waitcnt lgkmcnt(1)
	v_mfma_f32_32x32x16_bf16 v[16:31], v[206:209], v[228:231], v[16:31]
	s_waitcnt lgkmcnt(0)
	v_mfma_f32_32x32x16_bf16 v[0:15], v[244:247], v[228:231], v[0:15]
.Lfa_rare2:
	s_nop 7
	v_max_f32_e32 v144, v144, v144
	v_max_f32_e32 v144, 0, v144
	v_exp_f32_e64 v168, -v144
	v_add_f32_e32 v242, v242, v144
	v_pk_add_f32 v[80:81], v[80:81], v[144:145] op_sel_hi:[1,0] neg_lo:[0,1] neg_hi:[0,1]
	v_pk_add_f32 v[82:83], v[82:83], v[144:145] op_sel_hi:[1,0] neg_lo:[0,1] neg_hi:[0,1]
	v_pk_add_f32 v[84:85], v[84:85], v[144:145] op_sel_hi:[1,0] neg_lo:[0,1] neg_hi:[0,1]
	v_pk_add_f32 v[86:87], v[86:87], v[144:145] op_sel_hi:[1,0] neg_lo:[0,1] neg_hi:[0,1]
	v_pk_add_f32 v[88:89], v[88:89], v[144:145] op_sel_hi:[1,0] neg_lo:[0,1] neg_hi:[0,1]
	v_pk_add_f32 v[90:91], v[90:91], v[144:145] op_sel_hi:[1,0] neg_lo:[0,1] neg_hi:[0,1]
	v_pk_add_f32 v[92:93], v[92:93], v[144:145] op_sel_hi:[1,0] neg_lo:[0,1] neg_hi:[0,1]
	v_pk_add_f32 v[94:95], v[94:95], v[144:145] op_sel_hi:[1,0] neg_lo:[0,1] neg_hi:[0,1]
	v_pk_add_f32 v[64:65], v[64:65], v[144:145] op_sel_hi:[1,0] neg_lo:[0,1] neg_hi:[0,1]
	v_pk_add_f32 v[66:67], v[66:67], v[144:145] op_sel_hi:[1,0] neg_lo:[0,1] neg_hi:[0,1]
	v_pk_add_f32 v[68:69], v[68:69], v[144:145] op_sel_hi:[1,0] neg_lo:[0,1] neg_hi:[0,1]
	v_pk_add_f32 v[70:71], v[70:71], v[144:145] op_sel_hi:[1,0] neg_lo:[0,1] neg_hi:[0,1]
	v_pk_add_f32 v[72:73], v[72:73], v[144:145] op_sel_hi:[1,0] neg_lo:[0,1] neg_hi:[0,1]
	v_pk_add_f32 v[74:75], v[74:75], v[144:145] op_sel_hi:[1,0] neg_lo:[0,1] neg_hi:[0,1]
	v_pk_add_f32 v[76:77], v[76:77], v[144:145] op_sel_hi:[1,0] neg_lo:[0,1] neg_hi:[0,1]
	v_pk_add_f32 v[78:79], v[78:79], v[144:145] op_sel_hi:[1,0] neg_lo:[0,1] neg_hi:[0,1]
	v_pk_mul_f32 v[62:63], v[62:63], v[168:169] op_sel_hi:[1,0]
	v_pk_mul_f32 v[60:61], v[60:61], v[168:169] op_sel_hi:[1,0]
	v_pk_mul_f32 v[58:59], v[58:59], v[168:169] op_sel_hi:[1,0]
	v_pk_mul_f32 v[56:57], v[56:57], v[168:169] op_sel_hi:[1,0]
	v_pk_mul_f32 v[54:55], v[54:55], v[168:169] op_sel_hi:[1,0]
	v_pk_mul_f32 v[52:53], v[52:53], v[168:169] op_sel_hi:[1,0]
	v_pk_mul_f32 v[50:51], v[50:51], v[168:169] op_sel_hi:[1,0]
	v_pk_mul_f32 v[48:49], v[48:49], v[168:169] op_sel_hi:[1,0]
	v_pk_mul_f32 v[46:47], v[46:47], v[168:169] op_sel_hi:[1,0]
	v_pk_mul_f32 v[44:45], v[44:45], v[168:169] op_sel_hi:[1,0]
	v_pk_mul_f32 v[42:43], v[42:43], v[168:169] op_sel_hi:[1,0]
	v_pk_mul_f32 v[40:41], v[40:41], v[168:169] op_sel_hi:[1,0]
	v_pk_mul_f32 v[38:39], v[38:39], v[168:169] op_sel_hi:[1,0]
	v_pk_mul_f32 v[36:37], v[36:37], v[168:169] op_sel_hi:[1,0]
	v_pk_mul_f32 v[34:35], v[34:35], v[168:169] op_sel_hi:[1,0]
	v_pk_mul_f32 v[32:33], v[32:33], v[168:169] op_sel_hi:[1,0]
	v_pk_mul_f32 v[30:31], v[30:31], v[168:169] op_sel_hi:[1,0]
	v_pk_mul_f32 v[28:29], v[28:29], v[168:169] op_sel_hi:[1,0]
	v_pk_mul_f32 v[26:27], v[26:27], v[168:169] op_sel_hi:[1,0]
	v_pk_mul_f32 v[24:25], v[24:25], v[168:169] op_sel_hi:[1,0]
	v_pk_mul_f32 v[22:23], v[22:23], v[168:169] op_sel_hi:[1,0]
	v_pk_mul_f32 v[20:21], v[20:21], v[168:169] op_sel_hi:[1,0]
	v_pk_mul_f32 v[18:19], v[18:19], v[168:169] op_sel_hi:[1,0]
	v_pk_mul_f32 v[16:17], v[16:17], v[168:169] op_sel_hi:[1,0]
	v_pk_mul_f32 v[14:15], v[14:15], v[168:169] op_sel_hi:[1,0]
	v_pk_mul_f32 v[12:13], v[12:13], v[168:169] op_sel_hi:[1,0]
	v_pk_mul_f32 v[10:11], v[10:11], v[168:169] op_sel_hi:[1,0]
	v_pk_mul_f32 v[8:9], v[8:9], v[168:169] op_sel_hi:[1,0]
	v_pk_mul_f32 v[6:7], v[6:7], v[168:169] op_sel_hi:[1,0]
	v_pk_mul_f32 v[4:5], v[4:5], v[168:169] op_sel_hi:[1,0]
	v_pk_mul_f32 v[2:3], v[2:3], v[168:169] op_sel_hi:[1,0]
	v_pk_mul_f32 v[0:1], v[0:1], v[168:169] op_sel_hi:[1,0]
	v_mul_f32_e32 v184, v184, v168
	v_pk_mul_f32 v[194:195], v[194:195], v[168:169] op_sel_hi:[1,0]
	v_pk_mul_f32 v[196:197], v[196:197], v[168:169] op_sel_hi:[1,0]
	v_exp_f32_e32 v168, v80
	v_exp_f32_e32 v169, v81
	v_exp_f32_e32 v170, v82
	v_exp_f32_e32 v171, v83
	v_exp_f32_e32 v172, v84
	v_exp_f32_e32 v173, v85
	v_exp_f32_e32 v174, v86
	v_exp_f32_e32 v175, v87
	v_exp_f32_e32 v176, v88
	v_exp_f32_e32 v177, v89
	v_exp_f32_e32 v178, v90
	v_exp_f32_e32 v179, v91
	v_exp_f32_e32 v180, v92
	v_exp_f32_e32 v181, v93
	v_exp_f32_e32 v182, v94
	v_exp_f32_e32 v183, v95
	v_exp_f32_e32 v64, v64
	v_exp_f32_e32 v65, v65
	v_exp_f32_e32 v66, v66
	v_exp_f32_e32 v67, v67
	v_exp_f32_e32 v68, v68
	v_exp_f32_e32 v69, v69
	v_exp_f32_e32 v70, v70
	v_exp_f32_e32 v71, v71
	v_exp_f32_e32 v72, v72
	v_exp_f32_e32 v73, v73
	v_exp_f32_e32 v74, v74
	v_exp_f32_e32 v75, v75
	v_exp_f32_e32 v76, v76
	v_exp_f32_e32 v77, v77
	v_exp_f32_e32 v78, v78
	v_exp_f32_e32 v79, v79
	v_cvt_pk_bf16_f32 v216, v168, v169
	v_cvt_pk_bf16_f32 v217, v170, v171
	v_cvt_pk_bf16_f32 v218, v172, v173
	v_cvt_pk_bf16_f32 v219, v174, v175
	v_cvt_pk_bf16_f32 v220, v176, v177
	v_cvt_pk_bf16_f32 v221, v178, v179
	v_cvt_pk_bf16_f32 v222, v180, v181
	v_cvt_pk_bf16_f32 v223, v182, v183
	v_cvt_pk_bf16_f32 v224, v64, v65
	v_cvt_pk_bf16_f32 v225, v66, v67
	v_cvt_pk_bf16_f32 v226, v68, v69
	v_cvt_pk_bf16_f32 v227, v70, v71
	v_cvt_pk_bf16_f32 v228, v72, v73
	v_cvt_pk_bf16_f32 v229, v74, v75
	v_cvt_pk_bf16_f32 v230, v76, v77
	v_cvt_pk_bf16_f32 v231, v78, v79
	v_pk_add_f32 v[168:169], v[168:169], 0 op_sel_hi:[1,0]
	s_nop 0
	v_pk_add_f32 v[168:169], v[168:169], v[170:171]
	s_nop 0
	v_pk_add_f32 v[168:169], v[168:169], v[172:173]
	s_nop 0
	v_pk_add_f32 v[168:169], v[174:175], v[168:169]
	s_nop 0
	v_pk_add_f32 v[168:169], v[176:177], v[168:169]
	s_nop 0
	v_pk_add_f32 v[168:169], v[178:179], v[168:169]
	s_nop 0
	v_pk_add_f32 v[168:169], v[180:181], v[168:169]
	s_nop 0
	v_pk_add_f32 v[168:169], v[182:183], v[168:169]
	s_nop 0
	v_pk_add_f32 v[64:65], v[64:65], v[168:169]
	s_nop 0
	v_pk_add_f32 v[64:65], v[66:67], v[64:65]
	s_nop 0
	v_pk_add_f32 v[64:65], v[68:69], v[64:65]
	s_nop 0
	v_pk_add_f32 v[64:65], v[70:71], v[64:65]
	s_nop 0
	v_pk_add_f32 v[64:65], v[72:73], v[64:65]
	s_nop 0
	v_pk_add_f32 v[64:65], v[74:75], v[64:65]
	s_nop 0
	v_pk_add_f32 v[64:65], v[76:77], v[64:65]
	s_nop 0
	v_pk_add_f32 v[64:65], v[78:79], v[64:65]
	s_nop 0
	v_add_f32_e32 v64, v64, v65
	v_add_f32_e32 v184, v184, v64
	s_mov_b32 s88, 1
	s_branch .LBB0_1332
.Lfa_noqk:
	s_cmp_eq_u32 s88, 0
	s_cbranch_scc1 .LBB0_1332
	s_mul_i32 s33, s87, 0x4800
	v_add_u32_e32 v243, s33, v151
	ds_read_b128 v[232:235], v243 offset:51200
	ds_read_b128 v[202:205], v243 offset:55808
	ds_read_b128 v[206:209], v243 offset:60416
	ds_read_b128 v[244:247], v243 offset:65024
	s_waitcnt lgkmcnt(3)
	v_mfma_f32_32x32x16_bf16 v[48:63], v[232:235], v[216:219], v[48:63]
	ds_read_b128 v[232:235], v243 offset:51232
	s_waitcnt lgkmcnt(3)
	v_mfma_f32_32x32x16_bf16 v[32:47], v[202:205], v[216:219], v[32:47]
	ds_read_b128 v[202:205], v243 offset:55840
	s_waitcnt lgkmcnt(3)
	v_mfma_f32_32x32x16_bf16 v[16:31], v[206:209], v[216:219], v[16:31]
	ds_read_b128 v[206:209], v243 offset:60448
	s_waitcnt lgkmcnt(3)
	v_mfma_f32_32x32x16_bf16 v[0:15], v[244:247], v[216:219], v[0:15]
	ds_read_b128 v[244:247], v243 offset:65056
	s_waitcnt lgkmcnt(3)
	v_mfma_f32_32x32x16_bf16 v[48:63], v[232:235], v[220:223], v[48:63]
	ds_read_b128 v[232:235], v243 offset:51264
	s_waitcnt lgkmcnt(3)
	v_mfma_f32_32x32x16_bf16 v[32:47], v[202:205], v[220:223], v[32:47]
	ds_read_b128 v[202:205], v243 offset:55872
	s_waitcnt lgkmcnt(3)
	v_mfma_f32_32x32x16_bf16 v[16:31], v[206:209], v[220:223], v[16:31]
	ds_read_b128 v[206:209], v243 offset:60480
	s_waitcnt lgkmcnt(3)
	v_mfma_f32_32x32x16_bf16 v[0:15], v[244:247], v[220:223], v[0:15]
	ds_read_b128 v[244:247], v243 offset:65088
	s_waitcnt lgkmcnt(3)
	v_mfma_f32_32x32x16_bf16 v[48:63], v[232:235], v[224:227], v[48:63]
	ds_read_b128 v[232:235], v243 offset:51296
	s_waitcnt lgkmcnt(3)
	v_mfma_f32_32x32x16_bf16 v[32:47], v[202:205], v[224:227], v[32:47]
	ds_read_b128 v[202:205], v243 offset:55904
	s_waitcnt lgkmcnt(3)
	v_mfma_f32_32x32x16_bf16 v[16:31], v[206:209], v[224:227], v[16:31]
	ds_read_b128 v[206:209], v243 offset:60512
	s_waitcnt lgkmcnt(3)
	v_mfma_f32_32x32x16_bf16 v[0:15], v[244:247], v[224:227], v[0:15]
	ds_read_b128 v[244:247], v243 offset:65120
	s_waitcnt lgkmcnt(3)
	v_mfma_f32_32x32x16_bf16 v[48:63], v[232:235], v[228:231], v[48:63]
	s_waitcnt lgkmcnt(2)
	v_mfma_f32_32x32x16_bf16 v[32:47], v[202:205], v[228:231], v[32:47]
	s_waitcnt lgkmcnt(1)
	v_mfma_f32_32x32x16_bf16 v[16:31], v[206:209], v[228:231], v[16:31]
	s_waitcnt lgkmcnt(0)
	v_mfma_f32_32x32x16_bf16 v[0:15], v[244:247], v[228:231], v[0:15]
	s_mov_b32 s88, 0

.LBB0_1340:
	s_cmp_eq_u32 s88, 0
	s_cbranch_scc1 .Lfa_exit2
	s_mul_i32 s33, s86, 0x4800
	v_add_u32_e32 v243, s33, v151
	ds_read_b128 v[232:235], v243 offset:51200
	ds_read_b128 v[202:205], v243 offset:55808
	ds_read_b128 v[206:209], v243 offset:60416
	ds_read_b128 v[244:247], v243 offset:65024
	s_waitcnt lgkmcnt(3)
	v_mfma_f32_32x32x16_bf16 v[48:63], v[232:235], v[216:219], v[48:63]
	ds_read_b128 v[232:235], v243 offset:51232
	s_waitcnt lgkmcnt(3)
	v_mfma_f32_32x32x16_bf16 v[32:47], v[202:205], v[216:219], v[32:47]
	ds_read_b128 v[202:205], v243 offset:55840
	s_waitcnt lgkmcnt(3)
	v_mfma_f32_32x32x16_bf16 v[16:31], v[206:209], v[216:219], v[16:31]
	ds_read_b128 v[206:209], v243 offset:60448
	s_waitcnt lgkmcnt(3)
	v_mfma_f32_32x32x16_bf16 v[0:15], v[244:247], v[216:219], v[0:15]
	ds_read_b128 v[244:247], v243 offset:65056
	s_waitcnt lgkmcnt(3)
	v_mfma_f32_32x32x16_bf16 v[48:63], v[232:235], v[220:223], v[48:63]
	ds_read_b128 v[232:235], v243 offset:51264
	s_waitcnt lgkmcnt(3)
	v_mfma_f32_32x32x16_bf16 v[32:47], v[202:205], v[220:223], v[32:47]
	ds_read_b128 v[202:205], v243 offset:55872
	s_waitcnt lgkmcnt(3)
	v_mfma_f32_32x32x16_bf16 v[16:31], v[206:209], v[220:223], v[16:31]
	ds_read_b128 v[206:209], v243 offset:60480
	s_waitcnt lgkmcnt(3)
	v_mfma_f32_32x32x16_bf16 v[0:15], v[244:247], v[220:223], v[0:15]
	ds_read_b128 v[244:247], v243 offset:65088
	s_waitcnt lgkmcnt(3)
	v_mfma_f32_32x32x16_bf16 v[48:63], v[232:235], v[224:227], v[48:63]
	ds_read_b128 v[232:235], v243 offset:51296
	s_waitcnt lgkmcnt(3)
	v_mfma_f32_32x32x16_bf16 v[32:47], v[202:205], v[224:227], v[32:47]
	ds_read_b128 v[202:205], v243 offset:55904
	s_waitcnt lgkmcnt(3)
	v_mfma_f32_32x32x16_bf16 v[16:31], v[206:209], v[224:227], v[16:31]
	ds_read_b128 v[206:209], v243 offset:60512
	s_waitcnt lgkmcnt(3)
	v_mfma_f32_32x32x16_bf16 v[0:15], v[244:247], v[224:227], v[0:15]
	ds_read_b128 v[244:247], v243 offset:65120
	s_waitcnt lgkmcnt(3)
	v_mfma_f32_32x32x16_bf16 v[48:63], v[232:235], v[228:231], v[48:63]
	s_waitcnt lgkmcnt(2)
	v_mfma_f32_32x32x16_bf16 v[32:47], v[202:205], v[228:231], v[32:47]
	s_waitcnt lgkmcnt(1)
	v_mfma_f32_32x32x16_bf16 v[16:31], v[206:209], v[228:231], v[16:31]
	s_waitcnt lgkmcnt(0)
	v_mfma_f32_32x32x16_bf16 v[0:15], v[244:247], v[228:231], v[0:15]
.Lfa_exit2:
	v_pk_add_f32 v[194:195], v[194:195], v[196:197]
	s_nop 1
	v_add_f32_e32 v194, v194, v195
	v_add_f32_e32 v184, v184, v194
	s_branch .LBB0_1220
